# peeled first K-loop iteration after each unit epilogue: first two counted vmcnt waits no longer drain the epilogue's stores (G1/G3/G67), plus pipelined conversion
# baseline (speedup 1.0000x reference)
.LBB0_412:
	s_andn2_b64 vcc, exec, s[6:7]
	s_cbranch_vccnz .LBB0_503
	s_mov_b32 s99, 0
	s_mov_b64 s[6:7], s[40:41]
	s_mov_b32 s67, s52
	s_mov_b64 s[20:21], s[42:43]
	s_mov_b32 s78, s63
	s_mov_b32 s8, s2
	v_mbcnt_lo_u32_b32 v0, -1, 0
	v_mbcnt_hi_u32_b32 v0, -1, v0
	s_cmpk_lt_i32 s67, 0x3a0
	v_lshl_add_u32 v10, s8, 6, v0
	s_cselect_b64 s[14:15], -1, 0
	s_cmpk_gt_i32 s67, 0x39f
	v_readfirstlane_b32 s18, v10
	s_cbranch_scc1 .LBB0_418
	s_cmpk_gt_i32 s67, 0x17f
	s_mov_b64 s[16:17], -1
	s_cbranch_scc0 .LBB0_416
	s_and_b32 s6, s67, 7
	s_add_i32 s7, s67, 0xfe80
	s_bfe_u32 s7, s7, 0xd0003
	s_mulk_i32 s6, 0x44
	s_add_i32 s7, s7, s6
	s_lshr_b32 s6, s7, 4
	s_and_b32 s9, s6, 0x3f8
	s_sub_i32 s6, 34, s9
	s_waitcnt lgkmcnt(0)
	s_min_u32 s10, s6, 8
	v_cvt_f32_ubyte0_e32 v0, s10
	v_rcp_iflag_f32_e32 v2, v0
	s_and_b32 s11, s7, 0x7f
	v_cvt_f32_ubyte0_e32 v3, s11
	s_mov_b64 s[16:17], 0
	v_mul_f32_e32 v2, v3, v2
	v_trunc_f32_e32 v2, v2
	v_cvt_u32_f32_e32 v4, v2
	v_fma_f32 v2, -v2, v0, v3
	v_cmp_ge_f32_e64 s[6:7], |v2|, v0
	s_cmp_lg_u64 s[6:7], 0
	v_readfirstlane_b32 s8, v4
	s_addc_u32 s6, s8, 0
	s_and_b32 s8, s6, 0xff
	s_mul_i32 s6, s6, s10
	s_sub_i32 s6, s11, s6
	s_and_b32 s6, s6, 0xff
	s_add_i32 s6, s9, s6

.LBB0_429:
	s_ashr_i32 s27, s26, 31
	s_lshl_b64 s[28:29], s[26:27], 18
	s_cmp_eq_u32 s44, 0
	s_cselect_b32 s9, s79, s83
	s_cselect_b32 s7, s80, s84
	s_cselect_b32 s21, s81, s77
	s_cselect_b32 s27, s82, s85
	s_add_u32 s28, s9, s28
	s_addc_u32 s29, s7, s29
	s_and_b64 s[30:31], s[22:23], exec
	s_cselect_b32 s7, s29, s37
	s_cselect_b32 s9, s28, s36
	s_ashr_i32 s25, s24, 31
	s_lshl_b64 s[30:31], s[24:25], 18
	s_add_u32 s30, s21, s30
	s_addc_u32 s31, s27, s31
	s_and_b64 s[38:39], s[22:23], exec
	s_cselect_b32 s21, s31, s35
	s_cselect_b32 s25, s30, s34
	s_add_u32 s27, s34, 0x100
	s_addc_u32 s45, s35, 0
	s_add_u32 s34, s36, 0x20080
	v_mov_b32_e32 v2, 0
	s_addc_u32 s35, s37, 0
	s_mov_b32 s48, -2
	v_mov_b32_e32 v3, v2
	v_mov_b32_e32 v4, v2
	v_mov_b32_e32 v5, v2
	v_mov_b32_e32 v6, v2
	v_mov_b32_e32 v7, v2
	v_mov_b32_e32 v8, v2
	v_mov_b32_e32 v9, v2
	v_mov_b32_e32 v18, v2
	v_mov_b32_e32 v19, v2
	v_mov_b32_e32 v20, v2
	v_mov_b32_e32 v21, v2
	v_mov_b32_e32 v22, v2
	v_mov_b32_e32 v23, v2
	v_mov_b32_e32 v24, v2
	v_mov_b32_e32 v25, v2
	v_mov_b32_e32 v34, v2
	v_mov_b32_e32 v35, v2
	v_mov_b32_e32 v36, v2
	v_mov_b32_e32 v37, v2
	v_mov_b32_e32 v38, v2
	v_mov_b32_e32 v39, v2
	v_mov_b32_e32 v40, v2
	v_mov_b32_e32 v41, v2
	v_mov_b32_e32 v50, v2
	v_mov_b32_e32 v51, v2
	v_mov_b32_e32 v52, v2
	v_mov_b32_e32 v53, v2
	v_mov_b32_e32 v54, v2
	v_mov_b32_e32 v55, v2
	v_mov_b32_e32 v56, v2
	v_mov_b32_e32 v57, v2
	v_mov_b32_e32 v10, v2
	v_mov_b32_e32 v11, v2
	v_mov_b32_e32 v12, v2
	v_mov_b32_e32 v13, v2
	v_mov_b32_e32 v14, v2
	v_mov_b32_e32 v15, v2
	v_mov_b32_e32 v16, v2
	v_mov_b32_e32 v17, v2
	v_mov_b32_e32 v26, v2
	v_mov_b32_e32 v27, v2
	v_mov_b32_e32 v28, v2
	v_mov_b32_e32 v29, v2
	v_mov_b32_e32 v30, v2
	v_mov_b32_e32 v31, v2
	v_mov_b32_e32 v32, v2
	v_mov_b32_e32 v33, v2
	v_mov_b32_e32 v42, v2
	v_mov_b32_e32 v43, v2
	v_mov_b32_e32 v44, v2
	v_mov_b32_e32 v45, v2
	v_mov_b32_e32 v46, v2
	v_mov_b32_e32 v47, v2
	v_mov_b32_e32 v48, v2
	v_mov_b32_e32 v49, v2
	v_mov_b32_e32 v58, v2
	v_mov_b32_e32 v59, v2
	v_mov_b32_e32 v60, v2
	v_mov_b32_e32 v61, v2
	v_mov_b32_e32 v62, v2
	v_mov_b32_e32 v63, v2
	v_mov_b32_e32 v64, v2
	v_mov_b32_e32 v65, v2
	v_mov_b32_e32 v66, v2
	v_mov_b32_e32 v67, v2
	v_mov_b32_e32 v68, v2
	v_mov_b32_e32 v69, v2
	v_mov_b32_e32 v70, v2
	v_mov_b32_e32 v71, v2
	v_mov_b32_e32 v72, v2
	v_mov_b32_e32 v73, v2
	v_mov_b32_e32 v82, v2
	v_mov_b32_e32 v83, v2
	v_mov_b32_e32 v84, v2
	v_mov_b32_e32 v85, v2
	v_mov_b32_e32 v86, v2
	v_mov_b32_e32 v87, v2
	v_mov_b32_e32 v88, v2
	v_mov_b32_e32 v89, v2
	s_waitcnt vmcnt(0)
	v_mov_b32_e32 v98, v2
	v_mov_b32_e32 v99, v2
	v_mov_b32_e32 v100, v2
	v_mov_b32_e32 v101, v2
	v_mov_b32_e32 v102, v2
	v_mov_b32_e32 v103, v2
	v_mov_b32_e32 v104, v2
	v_mov_b32_e32 v105, v2
	v_mov_b32_e32 v114, v2
	v_mov_b32_e32 v115, v2
	v_mov_b32_e32 v116, v2
	v_mov_b32_e32 v117, v2
	v_mov_b32_e32 v118, v2
	v_mov_b32_e32 v119, v2
	v_mov_b32_e32 v120, v2
	v_mov_b32_e32 v121, v2
	v_mov_b32_e32 v74, v2
	v_mov_b32_e32 v75, v2
	v_mov_b32_e32 v76, v2
	v_mov_b32_e32 v77, v2
	v_mov_b32_e32 v78, v2
	v_mov_b32_e32 v79, v2
	v_mov_b32_e32 v80, v2
	v_mov_b32_e32 v81, v2
	v_mov_b32_e32 v90, v2
	v_mov_b32_e32 v91, v2
	v_mov_b32_e32 v92, v2
	v_mov_b32_e32 v93, v2
	v_mov_b32_e32 v94, v2
	v_mov_b32_e32 v95, v2
	v_mov_b32_e32 v96, v2
	v_mov_b32_e32 v97, v2
	v_mov_b32_e32 v106, v2
	v_mov_b32_e32 v107, v2
	v_mov_b32_e32 v108, v2
	v_mov_b32_e32 v109, v2
	v_mov_b32_e32 v110, v2
	v_mov_b32_e32 v111, v2
	v_mov_b32_e32 v112, v2
	v_mov_b32_e32 v113, v2
	v_mov_b32_e32 v122, v2
	v_mov_b32_e32 v123, v2
	v_mov_b32_e32 v124, v2
	v_mov_b32_e32 v125, v2
	v_mov_b32_e32 v126, v2
	v_mov_b32_e32 v127, v2
	v_mov_b32_e32 v128, v2
	v_mov_b32_e32 v129, v2
	s_cmp_eq_u32 s99, 0
	s_cbranch_scc1 .LBB0_430
.Lpeel_G67:
	s_add_u32 s36, s34, 0xfffe0080
	s_addc_u32 s37, s35, -1
	s_add_i32 s49, 0, 0x10000
	s_cmp_eq_u32 s48, 4
	s_cselect_b32 s39, s7, s37
	s_cselect_b32 s38, s9, s36
	s_cselect_b32 s37, s21, s45
	s_cselect_b32 s36, s25, s27
	s_add_i32 s61, 0, 0x14000
	v_add_u32_e32 v142, s49, v216
	v_add_u32_e32 v158, s61, v216
	ds_read_b128 v[130:133], v142
	ds_read_b128 v[134:137], v142 offset:1024
	ds_read_b128 v[138:141], v142 offset:2048
	ds_read_b128 v[142:145], v142 offset:3072
	ds_read_b128 v[146:149], v158
	ds_read_b128 v[150:153], v158 offset:1024
	ds_read_b128 v[154:157], v158 offset:2048
	ds_read_b128 v[158:161], v158 offset:3072
	v_lshl_add_u64 v[202:203], s[34:35], 0, v[210:211]
	s_add_i32 m0, s87, 0xc000
	ds_read_b128 v[162:165], v221
	ds_read_b128 v[166:169], v221 offset:1024
	ds_read_b128 v[170:173], v221 offset:2048
	ds_read_b128 v[174:177], v221 offset:3072
	ds_read_b128 v[178:181], v221 offset:4096
	ds_read_b128 v[182:185], v221 offset:5120
	ds_read_b128 v[186:189], v221 offset:6144
	ds_read_b128 v[190:193], v221 offset:7168
	global_load_lds_dwordx4 v[202:203], off
	v_lshl_add_u64 v[202:203], s[34:35], 0, v[208:209]
	s_add_i32 m0, s87, 0xe000
	s_nop 0
	global_load_lds_dwordx4 v[202:203], off
	s_waitcnt vmcnt(24)
	s_waitcnt lgkmcnt(0)
	s_barrier
	s_setprio 1
	s_waitcnt lgkmcnt(0)
	v_mfma_f32_16x16x32_bf16 v[126:129], v[130:133], v[162:165], v[126:129]
	v_mfma_f32_16x16x32_bf16 v[122:125], v[138:141], v[162:165], v[122:125]
	v_mfma_f32_16x16x32_bf16 v[110:113], v[130:133], v[170:173], v[110:113]
	v_mfma_f32_16x16x32_bf16 v[106:109], v[138:141], v[170:173], v[106:109]
	v_mfma_f32_16x16x32_bf16 v[94:97], v[130:133], v[178:181], v[94:97]
	v_mfma_f32_16x16x32_bf16 v[90:93], v[138:141], v[178:181], v[90:93]
	v_mfma_f32_16x16x32_bf16 v[78:81], v[130:133], v[186:189], v[78:81]
	v_mfma_f32_16x16x32_bf16 v[74:77], v[138:141], v[186:189], v[74:77]
	v_mfma_f32_16x16x32_bf16 v[126:129], v[134:137], v[166:169], v[126:129]
	v_mfma_f32_16x16x32_bf16 v[122:125], v[142:145], v[166:169], v[122:125]
	v_mfma_f32_16x16x32_bf16 v[110:113], v[134:137], v[174:177], v[110:113]
	v_mfma_f32_16x16x32_bf16 v[106:109], v[142:145], v[174:177], v[106:109]
	v_mfma_f32_16x16x32_bf16 v[94:97], v[134:137], v[182:185], v[94:97]
	v_mfma_f32_16x16x32_bf16 v[90:93], v[142:145], v[182:185], v[90:93]
	v_mfma_f32_16x16x32_bf16 v[78:81], v[134:137], v[190:193], v[78:81]
	v_mfma_f32_16x16x32_bf16 v[74:77], v[142:145], v[190:193], v[74:77]
	s_setprio 0
	s_setprio 1
	v_mfma_f32_16x16x32_bf16 v[118:121], v[146:149], v[162:165], v[118:121]
	v_mfma_f32_16x16x32_bf16 v[114:117], v[154:157], v[162:165], v[114:117]
	v_mfma_f32_16x16x32_bf16 v[102:105], v[146:149], v[170:173], v[102:105]
	v_mfma_f32_16x16x32_bf16 v[98:101], v[154:157], v[170:173], v[98:101]
	v_mfma_f32_16x16x32_bf16 v[86:89], v[146:149], v[178:181], v[86:89]
	v_mfma_f32_16x16x32_bf16 v[82:85], v[154:157], v[178:181], v[82:85]
	v_mfma_f32_16x16x32_bf16 v[70:73], v[146:149], v[186:189], v[70:73]
	v_mfma_f32_16x16x32_bf16 v[66:69], v[154:157], v[186:189], v[66:69]
	v_mfma_f32_16x16x32_bf16 v[118:121], v[150:153], v[166:169], v[118:121]
	v_mfma_f32_16x16x32_bf16 v[114:117], v[158:161], v[166:169], v[114:117]
	v_mfma_f32_16x16x32_bf16 v[102:105], v[150:153], v[174:177], v[102:105]
	v_mfma_f32_16x16x32_bf16 v[98:101], v[158:161], v[174:177], v[98:101]
	v_mfma_f32_16x16x32_bf16 v[86:89], v[150:153], v[182:185], v[86:89]
	v_mfma_f32_16x16x32_bf16 v[82:85], v[158:161], v[182:185], v[82:85]
	v_mfma_f32_16x16x32_bf16 v[70:73], v[150:153], v[190:193], v[70:73]
	v_mfma_f32_16x16x32_bf16 v[66:69], v[158:161], v[190:193], v[66:69]
	s_setprio 0
	s_barrier
	s_add_i32 s49, s49, s86
	v_lshl_add_u64 v[202:203], s[36:37], 0, v[194:195]
	s_mov_b32 m0, s49
	ds_read_b128 v[162:165], v221 offset:16384
	ds_read_b128 v[166:169], v221 offset:17408
	ds_read_b128 v[170:173], v221 offset:18432
	ds_read_b128 v[174:177], v221 offset:19456
	ds_read_b128 v[178:181], v221 offset:20480
	ds_read_b128 v[182:185], v221 offset:21504
	ds_read_b128 v[186:189], v221 offset:22528
	ds_read_b128 v[190:193], v221 offset:23552
	global_load_lds_dwordx4 v[202:203], off
	s_add_i32 m0, s49, 0x2000
	s_add_u32 s94, s36, 0x20000
	v_lshl_add_u64 v[204:205], s[36:37], 0, v[196:197]
	s_addc_u32 s95, s37, 0
	s_add_i32 s49, s61, s86
	global_load_lds_dwordx4 v[204:205], off
	v_lshl_add_u64 v[206:207], s[94:95], 0, v[194:195]
	s_mov_b32 m0, s49
	v_lshl_add_u64 v[222:223], s[38:39], 0, v[196:197]
	global_load_lds_dwordx4 v[206:207], off
	v_lshl_add_u64 v[206:207], s[94:95], 0, v[196:197]
	s_add_i32 m0, s49, 0x2000
	s_nop 0
	global_load_lds_dwordx4 v[206:207], off
	v_lshl_add_u64 v[206:207], s[38:39], 0, v[194:195]
	s_mov_b32 m0, s87
	s_nop 0
	global_load_lds_dwordx4 v[206:207], off
	s_mov_b32 m0, s68
	s_nop 0
	global_load_lds_dwordx4 v[222:223], off
	s_waitcnt vmcnt(24)
	s_waitcnt lgkmcnt(0)
	s_barrier
	s_setprio 1
	s_waitcnt lgkmcnt(0)
	v_mfma_f32_16x16x32_bf16 v[62:65], v[130:133], v[162:165], v[62:65]
	v_mfma_f32_16x16x32_bf16 v[58:61], v[138:141], v[162:165], v[58:61]
	v_mfma_f32_16x16x32_bf16 v[46:49], v[130:133], v[170:173], v[46:49]
	v_mfma_f32_16x16x32_bf16 v[42:45], v[138:141], v[170:173], v[42:45]
	v_mfma_f32_16x16x32_bf16 v[30:33], v[130:133], v[178:181], v[30:33]
	v_mfma_f32_16x16x32_bf16 v[26:29], v[138:141], v[178:181], v[26:29]
	v_mfma_f32_16x16x32_bf16 v[14:17], v[130:133], v[186:189], v[14:17]
	v_mfma_f32_16x16x32_bf16 v[10:13], v[138:141], v[186:189], v[10:13]
	v_mfma_f32_16x16x32_bf16 v[62:65], v[134:137], v[166:169], v[62:65]
	v_mfma_f32_16x16x32_bf16 v[58:61], v[142:145], v[166:169], v[58:61]
	v_mfma_f32_16x16x32_bf16 v[46:49], v[134:137], v[174:177], v[46:49]
	v_mfma_f32_16x16x32_bf16 v[42:45], v[142:145], v[174:177], v[42:45]
	v_mfma_f32_16x16x32_bf16 v[30:33], v[134:137], v[182:185], v[30:33]
	v_mfma_f32_16x16x32_bf16 v[26:29], v[142:145], v[182:185], v[26:29]
	v_mfma_f32_16x16x32_bf16 v[14:17], v[134:137], v[190:193], v[14:17]
	v_mfma_f32_16x16x32_bf16 v[10:13], v[142:145], v[190:193], v[10:13]
	s_setprio 0
	s_setprio 1
	v_mfma_f32_16x16x32_bf16 v[54:57], v[146:149], v[162:165], v[54:57]
	v_mfma_f32_16x16x32_bf16 v[50:53], v[154:157], v[162:165], v[50:53]
	v_mfma_f32_16x16x32_bf16 v[38:41], v[146:149], v[170:173], v[38:41]
	v_mfma_f32_16x16x32_bf16 v[34:37], v[154:157], v[170:173], v[34:37]
	v_mfma_f32_16x16x32_bf16 v[22:25], v[146:149], v[178:181], v[22:25]
	v_mfma_f32_16x16x32_bf16 v[18:21], v[154:157], v[178:181], v[18:21]
	v_mfma_f32_16x16x32_bf16 v[6:9], v[146:149], v[186:189], v[6:9]
	v_mfma_f32_16x16x32_bf16 v[2:5], v[154:157], v[186:189], v[2:5]
	v_mfma_f32_16x16x32_bf16 v[54:57], v[150:153], v[166:169], v[54:57]
	v_mfma_f32_16x16x32_bf16 v[50:53], v[158:161], v[166:169], v[50:53]
	v_mfma_f32_16x16x32_bf16 v[38:41], v[150:153], v[174:177], v[38:41]
	v_mfma_f32_16x16x32_bf16 v[34:37], v[158:161], v[174:177], v[34:37]
	v_mfma_f32_16x16x32_bf16 v[22:25], v[150:153], v[182:185], v[22:25]
	v_mfma_f32_16x16x32_bf16 v[18:21], v[158:161], v[182:185], v[18:21]
	v_mfma_f32_16x16x32_bf16 v[6:9], v[150:153], v[190:193], v[6:9]
	v_mfma_f32_16x16x32_bf16 v[2:5], v[158:161], v[190:193], v[2:5]
	s_setprio 0
	s_barrier
	s_add_i32 s49, 0, 0x18000
	s_add_i32 s61, 0, 0x1c000
	v_add_u32_e32 v142, s49, v216
	v_add_u32_e32 v158, s61, v216
	ds_read_b128 v[130:133], v142
	ds_read_b128 v[134:137], v142 offset:1024
	ds_read_b128 v[138:141], v142 offset:2048
	ds_read_b128 v[142:145], v142 offset:3072
	ds_read_b128 v[146:149], v158
	ds_read_b128 v[150:153], v158 offset:1024
	ds_read_b128 v[154:157], v158 offset:2048
	ds_read_b128 v[158:161], v158 offset:3072
	s_add_u32 s38, s38, 0x20000
	s_addc_u32 s39, s39, 0
	s_mov_b32 m0, s69
	v_lshl_add_u64 v[226:227], s[38:39], 0, v[194:195]
	ds_read_b128 v[162:165], v221 offset:32768
	ds_read_b128 v[166:169], v221 offset:33792
	ds_read_b128 v[170:173], v221 offset:34816
	ds_read_b128 v[174:177], v221 offset:35840
	ds_read_b128 v[178:181], v221 offset:36864
	ds_read_b128 v[182:185], v221 offset:37888
	ds_read_b128 v[186:189], v221 offset:38912
	ds_read_b128 v[190:193], v221 offset:39936
	global_load_lds_dwordx4 v[226:227], off
	v_lshl_add_u64 v[226:227], s[38:39], 0, v[196:197]
	s_mov_b32 m0, s70
	s_nop 0
	global_load_lds_dwordx4 v[226:227], off
	s_waitcnt vmcnt(8)
	s_waitcnt lgkmcnt(0)
	s_barrier
	s_setprio 1
	s_waitcnt lgkmcnt(0)
	v_mfma_f32_16x16x32_bf16 v[126:129], v[130:133], v[162:165], v[126:129]
	v_mfma_f32_16x16x32_bf16 v[122:125], v[138:141], v[162:165], v[122:125]
	v_mfma_f32_16x16x32_bf16 v[110:113], v[130:133], v[170:173], v[110:113]
	v_mfma_f32_16x16x32_bf16 v[106:109], v[138:141], v[170:173], v[106:109]
	v_mfma_f32_16x16x32_bf16 v[94:97], v[130:133], v[178:181], v[94:97]
	v_mfma_f32_16x16x32_bf16 v[90:93], v[138:141], v[178:181], v[90:93]
	v_mfma_f32_16x16x32_bf16 v[78:81], v[130:133], v[186:189], v[78:81]
	v_mfma_f32_16x16x32_bf16 v[74:77], v[138:141], v[186:189], v[74:77]
	v_mfma_f32_16x16x32_bf16 v[126:129], v[134:137], v[166:169], v[126:129]
	v_mfma_f32_16x16x32_bf16 v[122:125], v[142:145], v[166:169], v[122:125]
	v_mfma_f32_16x16x32_bf16 v[110:113], v[134:137], v[174:177], v[110:113]
	v_mfma_f32_16x16x32_bf16 v[106:109], v[142:145], v[174:177], v[106:109]
	v_mfma_f32_16x16x32_bf16 v[94:97], v[134:137], v[182:185], v[94:97]
	v_mfma_f32_16x16x32_bf16 v[90:93], v[142:145], v[182:185], v[90:93]
	v_mfma_f32_16x16x32_bf16 v[78:81], v[134:137], v[190:193], v[78:81]
	v_mfma_f32_16x16x32_bf16 v[74:77], v[142:145], v[190:193], v[74:77]
	s_setprio 0
	s_setprio 1
	v_mfma_f32_16x16x32_bf16 v[118:121], v[146:149], v[162:165], v[118:121]
	v_mfma_f32_16x16x32_bf16 v[114:117], v[154:157], v[162:165], v[114:117]
	v_mfma_f32_16x16x32_bf16 v[102:105], v[146:149], v[170:173], v[102:105]
	v_mfma_f32_16x16x32_bf16 v[98:101], v[154:157], v[170:173], v[98:101]
	v_mfma_f32_16x16x32_bf16 v[86:89], v[146:149], v[178:181], v[86:89]
	v_mfma_f32_16x16x32_bf16 v[82:85], v[154:157], v[178:181], v[82:85]
	v_mfma_f32_16x16x32_bf16 v[70:73], v[146:149], v[186:189], v[70:73]
	v_mfma_f32_16x16x32_bf16 v[66:69], v[154:157], v[186:189], v[66:69]
	v_mfma_f32_16x16x32_bf16 v[118:121], v[150:153], v[166:169], v[118:121]
	v_mfma_f32_16x16x32_bf16 v[114:117], v[158:161], v[166:169], v[114:117]
	v_mfma_f32_16x16x32_bf16 v[102:105], v[150:153], v[174:177], v[102:105]
	v_mfma_f32_16x16x32_bf16 v[98:101], v[158:161], v[174:177], v[98:101]
	v_mfma_f32_16x16x32_bf16 v[86:89], v[150:153], v[182:185], v[86:89]
	v_mfma_f32_16x16x32_bf16 v[82:85], v[158:161], v[182:185], v[82:85]
	v_mfma_f32_16x16x32_bf16 v[70:73], v[150:153], v[190:193], v[70:73]
	v_mfma_f32_16x16x32_bf16 v[66:69], v[158:161], v[190:193], v[66:69]
	s_setprio 0
	s_barrier
	s_add_i32 s38, s49, s86
	v_lshl_add_u64 v[202:203], v[202:203], 0, s[54:55]
	s_mov_b32 m0, s38
	ds_read_b128 v[162:165], v221 offset:49152
	ds_read_b128 v[166:169], v221 offset:50176
	ds_read_b128 v[170:173], v221 offset:51200
	ds_read_b128 v[174:177], v221 offset:52224
	ds_read_b128 v[178:181], v221 offset:53248
	ds_read_b128 v[182:185], v221 offset:54272
	ds_read_b128 v[186:189], v221 offset:55296
	ds_read_b128 v[190:193], v221 offset:56320
	global_load_lds_dwordx4 v[202:203], off
	s_add_i32 m0, s38, 0x2000
	s_add_u32 s36, s36, 0x20080
	v_lshl_add_u64 v[202:203], v[204:205], 0, s[54:55]
	s_addc_u32 s37, s37, 0
	s_add_i32 s38, s61, s86
	global_load_lds_dwordx4 v[202:203], off
	v_lshl_add_u64 v[202:203], s[36:37], 0, v[194:195]
	s_mov_b32 m0, s38
	s_nop 0
	global_load_lds_dwordx4 v[202:203], off
	v_lshl_add_u64 v[202:203], s[36:37], 0, v[196:197]
	s_add_i32 m0, s38, 0x2000
	s_nop 0
	global_load_lds_dwordx4 v[202:203], off
	v_lshl_add_u64 v[202:203], v[206:207], 0, s[54:55]
	s_mov_b32 m0, s73
	s_nop 0
	global_load_lds_dwordx4 v[202:203], off
	v_lshl_add_u64 v[202:203], v[222:223], 0, s[54:55]
	s_mov_b32 m0, s89
	s_nop 0
	global_load_lds_dwordx4 v[202:203], off
	s_waitcnt vmcnt(8)
	s_waitcnt lgkmcnt(0)
	s_barrier
	s_setprio 1
	s_waitcnt lgkmcnt(0)
	v_mfma_f32_16x16x32_bf16 v[62:65], v[130:133], v[162:165], v[62:65]
	v_mfma_f32_16x16x32_bf16 v[58:61], v[138:141], v[162:165], v[58:61]
	v_mfma_f32_16x16x32_bf16 v[46:49], v[130:133], v[170:173], v[46:49]
	v_mfma_f32_16x16x32_bf16 v[42:45], v[138:141], v[170:173], v[42:45]
	v_mfma_f32_16x16x32_bf16 v[30:33], v[130:133], v[178:181], v[30:33]
	v_mfma_f32_16x16x32_bf16 v[26:29], v[138:141], v[178:181], v[26:29]
	v_mfma_f32_16x16x32_bf16 v[14:17], v[130:133], v[186:189], v[14:17]
	v_mfma_f32_16x16x32_bf16 v[10:13], v[138:141], v[186:189], v[10:13]
	v_mfma_f32_16x16x32_bf16 v[62:65], v[134:137], v[166:169], v[62:65]
	v_mfma_f32_16x16x32_bf16 v[58:61], v[142:145], v[166:169], v[58:61]
	v_mfma_f32_16x16x32_bf16 v[46:49], v[134:137], v[174:177], v[46:49]
	v_mfma_f32_16x16x32_bf16 v[42:45], v[142:145], v[174:177], v[42:45]
	v_mfma_f32_16x16x32_bf16 v[30:33], v[134:137], v[182:185], v[30:33]
	v_mfma_f32_16x16x32_bf16 v[26:29], v[142:145], v[182:185], v[26:29]
	v_mfma_f32_16x16x32_bf16 v[14:17], v[134:137], v[190:193], v[14:17]
	v_mfma_f32_16x16x32_bf16 v[10:13], v[142:145], v[190:193], v[10:13]
	s_setprio 0
	s_setprio 1
	v_mfma_f32_16x16x32_bf16 v[54:57], v[146:149], v[162:165], v[54:57]
	v_mfma_f32_16x16x32_bf16 v[50:53], v[154:157], v[162:165], v[50:53]
	v_mfma_f32_16x16x32_bf16 v[38:41], v[146:149], v[170:173], v[38:41]
	v_mfma_f32_16x16x32_bf16 v[34:37], v[154:157], v[170:173], v[34:37]
	v_mfma_f32_16x16x32_bf16 v[22:25], v[146:149], v[178:181], v[22:25]
	v_mfma_f32_16x16x32_bf16 v[18:21], v[154:157], v[178:181], v[18:21]
	v_mfma_f32_16x16x32_bf16 v[6:9], v[146:149], v[186:189], v[6:9]
	v_mfma_f32_16x16x32_bf16 v[2:5], v[154:157], v[186:189], v[2:5]
	v_mfma_f32_16x16x32_bf16 v[54:57], v[150:153], v[166:169], v[54:57]
	v_mfma_f32_16x16x32_bf16 v[50:53], v[158:161], v[166:169], v[50:53]
	v_mfma_f32_16x16x32_bf16 v[38:41], v[150:153], v[174:177], v[38:41]
	v_mfma_f32_16x16x32_bf16 v[34:37], v[158:161], v[174:177], v[34:37]
	v_mfma_f32_16x16x32_bf16 v[22:25], v[150:153], v[182:185], v[22:25]
	v_mfma_f32_16x16x32_bf16 v[18:21], v[158:161], v[182:185], v[18:21]
	v_mfma_f32_16x16x32_bf16 v[6:9], v[150:153], v[190:193], v[6:9]
	v_mfma_f32_16x16x32_bf16 v[2:5], v[158:161], v[190:193], v[2:5]
	s_setprio 0
	s_barrier
	s_add_i32 s48, s48, 2
	s_add_u32 s27, s27, 0x100
	s_addc_u32 s45, s45, 0
	s_add_u32 s34, s34, 0x100
	s_addc_u32 s35, s35, 0
	s_cmp_gt_u32 s48, 5
	s_cbranch_scc1 .Lpeel_exit_G67

.Lpeel_exit_G67:
	s_mov_b32 s99, 1
	s_and_b64 vcc, exec, s[18:19]
	s_cbranch_vccz .LBB0_433
	s_barrier

.LBB0_593:
	s_andn2_b64 vcc, exec, s[4:5]
	s_cbranch_vccnz .LBB0_774
	s_mov_b32 s99, 0
	s_mov_b64 s[4:5], s[40:41]
	s_mov_b32 s69, s52
	s_mov_b64 s[14:15], s[42:43]
	s_mov_b32 s68, s63
	s_mov_b32 s6, s2
	s_cmpk_lt_i32 s69, 0x180
	v_mbcnt_lo_u32_b32 v226, -1, 0
	v_mbcnt_hi_u32_b32 v226, -1, v226
	s_nop 0
	v_lshl_add_u32 v10, s6, 6, v226
	s_cselect_b64 s[6:7], -1, 0
	s_ashr_i32 s71, s69, 31
	v_readfirstlane_b32 s70, v10
	s_cmpk_gt_i32 s69, 0x17f
	s_nop 0
	v_readfirstlane_b32 s30, v10
	s_cbranch_scc1 .LBB0_596
	s_ashr_i32 s8, s69, 31
	s_lshr_b32 s8, s8, 29
	s_add_i32 s8, s69, s8
	s_ashr_i32 s9, s8, 3
	s_and_b32 s8, s8, -8
	s_sub_i32 s8, s69, s8
	s_cmp_lt_i32 s8, 0
	s_waitcnt lgkmcnt(0)
	s_cselect_b32 s10, 49, 48
	s_mul_i32 s8, s8, s10
	s_add_i32 s8, s8, s9
	s_mul_hi_i32 s9, s8, 0x2aaaaaab
	s_lshr_b32 s10, s9, 31
	s_ashr_i32 s9, s9, 4
	s_add_i32 s9, s9, s10
	s_lshl_b32 s10, s9, 3
	s_mulk_i32 s9, 0x60
	s_sub_i32 s8, s8, s9
	s_bfe_i32 s9, s8, 0x80000
	s_bfe_u32 s9, s9, 0x3000c
	s_add_i32 s9, s8, s9
	s_bfe_i32 s11, s9, 0x80000
	s_and_b32 s9, s9, 0xf8
	s_sub_i32 s8, s8, s9
	s_sext_i32_i16 s11, s11
	s_sext_i32_i8 s8, s8
	s_add_i32 s78, s10, s8
	s_ashr_i32 s10, s11, 3

.LBB0_604:
	s_ashr_i32 s35, s34, 31
	s_lshl_b64 s[36:37], s[34:35], 20
	s_add_u32 s36, s73, s36
	s_addc_u32 s37, s89, s37
	s_and_b64 s[38:39], s[6:7], exec
	s_cselect_b32 s11, s37, s81
	s_cselect_b32 s35, s36, s80
	s_ashr_i32 s31, s30, 31
	s_lshl_b64 s[38:39], s[30:31], 20
	s_add_u32 s38, s97, s38
	s_addc_u32 s39, s65, s39
	s_and_b64 s[82:83], s[6:7], exec
	s_cselect_b32 s31, s39, s9
	s_cselect_b32 s79, s38, s8
	s_add_u32 s84, s8, 0x100
	s_addc_u32 s85, s9, 0
	s_add_u32 s8, s80, 0x80080
	v_mov_b32_e32 v2, 0
	s_addc_u32 s9, s81, 0
	s_mov_b32 s86, -2
	v_mov_b32_e32 v3, v2
	v_mov_b32_e32 v4, v2
	v_mov_b32_e32 v5, v2
	v_mov_b32_e32 v6, v2
	v_mov_b32_e32 v7, v2
	v_mov_b32_e32 v8, v2
	v_mov_b32_e32 v9, v2
	v_mov_b32_e32 v18, v2
	v_mov_b32_e32 v19, v2
	v_mov_b32_e32 v20, v2
	v_mov_b32_e32 v21, v2
	v_mov_b32_e32 v22, v2
	v_mov_b32_e32 v23, v2
	v_mov_b32_e32 v24, v2
	v_mov_b32_e32 v25, v2
	v_mov_b32_e32 v34, v2
	v_mov_b32_e32 v35, v2
	v_mov_b32_e32 v36, v2
	v_mov_b32_e32 v37, v2
	v_mov_b32_e32 v38, v2
	v_mov_b32_e32 v39, v2
	v_mov_b32_e32 v40, v2
	v_mov_b32_e32 v41, v2
	v_mov_b32_e32 v50, v2
	v_mov_b32_e32 v51, v2
	v_mov_b32_e32 v52, v2
	v_mov_b32_e32 v53, v2
	v_mov_b32_e32 v54, v2
	v_mov_b32_e32 v55, v2
	v_mov_b32_e32 v56, v2
	v_mov_b32_e32 v57, v2
	v_mov_b32_e32 v10, v2
	v_mov_b32_e32 v11, v2
	v_mov_b32_e32 v12, v2
	v_mov_b32_e32 v13, v2
	v_mov_b32_e32 v14, v2
	v_mov_b32_e32 v15, v2
	v_mov_b32_e32 v16, v2
	v_mov_b32_e32 v17, v2
	v_mov_b32_e32 v26, v2
	v_mov_b32_e32 v27, v2
	v_mov_b32_e32 v28, v2
	v_mov_b32_e32 v29, v2
	v_mov_b32_e32 v30, v2
	v_mov_b32_e32 v31, v2
	v_mov_b32_e32 v32, v2
	v_mov_b32_e32 v33, v2
	v_mov_b32_e32 v42, v2
	v_mov_b32_e32 v43, v2
	v_mov_b32_e32 v44, v2
	v_mov_b32_e32 v45, v2
	v_mov_b32_e32 v46, v2
	v_mov_b32_e32 v47, v2
	v_mov_b32_e32 v48, v2
	v_mov_b32_e32 v49, v2
	v_mov_b32_e32 v58, v2
	v_mov_b32_e32 v59, v2
	v_mov_b32_e32 v60, v2
	v_mov_b32_e32 v61, v2
	v_mov_b32_e32 v62, v2
	v_mov_b32_e32 v63, v2
	v_mov_b32_e32 v64, v2
	v_mov_b32_e32 v65, v2
	v_mov_b32_e32 v66, v2
	v_mov_b32_e32 v67, v2
	v_mov_b32_e32 v68, v2
	v_mov_b32_e32 v69, v2
	v_mov_b32_e32 v70, v2
	v_mov_b32_e32 v71, v2
	v_mov_b32_e32 v72, v2
	v_mov_b32_e32 v73, v2
	v_mov_b32_e32 v82, v2
	v_mov_b32_e32 v83, v2
	v_mov_b32_e32 v84, v2
	v_mov_b32_e32 v85, v2
	v_mov_b32_e32 v86, v2
	v_mov_b32_e32 v87, v2
	v_mov_b32_e32 v88, v2
	v_mov_b32_e32 v89, v2
	s_waitcnt vmcnt(0)
	v_mov_b32_e32 v98, v2
	v_mov_b32_e32 v99, v2
	v_mov_b32_e32 v100, v2
	v_mov_b32_e32 v101, v2
	v_mov_b32_e32 v102, v2
	v_mov_b32_e32 v103, v2
	v_mov_b32_e32 v104, v2
	v_mov_b32_e32 v105, v2
	v_mov_b32_e32 v114, v2
	v_mov_b32_e32 v115, v2
	v_mov_b32_e32 v116, v2
	v_mov_b32_e32 v117, v2
	v_mov_b32_e32 v118, v2
	v_mov_b32_e32 v119, v2
	v_mov_b32_e32 v120, v2
	v_mov_b32_e32 v121, v2
	v_mov_b32_e32 v74, v2
	v_mov_b32_e32 v75, v2
	v_mov_b32_e32 v76, v2
	v_mov_b32_e32 v77, v2
	v_mov_b32_e32 v78, v2
	v_mov_b32_e32 v79, v2
	v_mov_b32_e32 v80, v2
	v_mov_b32_e32 v81, v2
	v_mov_b32_e32 v90, v2
	v_mov_b32_e32 v91, v2
	v_mov_b32_e32 v92, v2
	v_mov_b32_e32 v93, v2
	v_mov_b32_e32 v94, v2
	v_mov_b32_e32 v95, v2
	v_mov_b32_e32 v96, v2
	v_mov_b32_e32 v97, v2
	v_mov_b32_e32 v106, v2
	v_mov_b32_e32 v107, v2
	v_mov_b32_e32 v108, v2
	v_mov_b32_e32 v109, v2
	v_mov_b32_e32 v110, v2
	v_mov_b32_e32 v111, v2
	v_mov_b32_e32 v112, v2
	v_mov_b32_e32 v113, v2
	v_mov_b32_e32 v122, v2
	v_mov_b32_e32 v123, v2
	v_mov_b32_e32 v124, v2
	v_mov_b32_e32 v125, v2
	v_mov_b32_e32 v130, v2
	v_mov_b32_e32 v131, v2
	v_mov_b32_e32 v132, v2
	v_mov_b32_e32 v133, v2
	s_waitcnt vmcnt(0)
	s_cmp_eq_u32 s99, 0
	s_cbranch_scc1 .LBB0_605
.Lpeel_G1:
	s_add_u32 s80, s8, 0xfff80080
	s_addc_u32 s81, s9, -1
	s_add_i32 s87, 0, 0x10000
	s_cmp_eq_u32 s86, 28
	s_cselect_b32 s83, s11, s81
	s_cselect_b32 s82, s35, s80
	s_cselect_b32 s81, s31, s85
	s_cselect_b32 s80, s79, s84
	s_add_i32 s92, 0, 0x14000
	v_add_u32_e32 v142, s87, v228
	v_add_u32_e32 v158, s92, v228
	ds_read_b128 v[126:129], v142
	ds_read_b128 v[134:137], v142 offset:1024
	ds_read_b128 v[138:141], v142 offset:2048
	ds_read_b128 v[142:145], v142 offset:3072
	ds_read_b128 v[146:149], v158
	ds_read_b128 v[150:153], v158 offset:1024
	ds_read_b128 v[154:157], v158 offset:2048
	ds_read_b128 v[158:161], v158 offset:3072
	v_lshl_add_u64 v[202:203], s[8:9], 0, v[210:211]
	s_add_i32 m0, s61, 0xc000
	ds_read_b128 v[162:165], v233
	ds_read_b128 v[166:169], v233 offset:1024
	ds_read_b128 v[170:173], v233 offset:2048
	ds_read_b128 v[174:177], v233 offset:3072
	ds_read_b128 v[178:181], v233 offset:4096
	ds_read_b128 v[182:185], v233 offset:5120
	ds_read_b128 v[186:189], v233 offset:6144
	ds_read_b128 v[190:193], v233 offset:7168
	global_load_lds_dwordx4 v[202:203], off
	v_lshl_add_u64 v[202:203], s[8:9], 0, v[208:209]
	s_add_i32 m0, s61, 0xe000
	s_nop 0
	global_load_lds_dwordx4 v[202:203], off
	s_waitcnt vmcnt(24)
	s_waitcnt lgkmcnt(0)
	s_barrier
	s_setprio 1
	s_waitcnt lgkmcnt(0)
	v_mfma_f32_16x16x32_bf16 v[130:133], v[126:129], v[162:165], v[130:133]
	v_mfma_f32_16x16x32_bf16 v[122:125], v[138:141], v[162:165], v[122:125]
	v_mfma_f32_16x16x32_bf16 v[110:113], v[126:129], v[170:173], v[110:113]
	v_mfma_f32_16x16x32_bf16 v[106:109], v[138:141], v[170:173], v[106:109]
	v_mfma_f32_16x16x32_bf16 v[94:97], v[126:129], v[178:181], v[94:97]
	v_mfma_f32_16x16x32_bf16 v[90:93], v[138:141], v[178:181], v[90:93]
	v_mfma_f32_16x16x32_bf16 v[78:81], v[126:129], v[186:189], v[78:81]
	v_mfma_f32_16x16x32_bf16 v[74:77], v[138:141], v[186:189], v[74:77]
	v_mfma_f32_16x16x32_bf16 v[130:133], v[134:137], v[166:169], v[130:133]
	v_mfma_f32_16x16x32_bf16 v[122:125], v[142:145], v[166:169], v[122:125]
	v_mfma_f32_16x16x32_bf16 v[110:113], v[134:137], v[174:177], v[110:113]
	v_mfma_f32_16x16x32_bf16 v[106:109], v[142:145], v[174:177], v[106:109]
	v_mfma_f32_16x16x32_bf16 v[94:97], v[134:137], v[182:185], v[94:97]
	v_mfma_f32_16x16x32_bf16 v[90:93], v[142:145], v[182:185], v[90:93]
	v_mfma_f32_16x16x32_bf16 v[78:81], v[134:137], v[190:193], v[78:81]
	v_mfma_f32_16x16x32_bf16 v[74:77], v[142:145], v[190:193], v[74:77]
	s_setprio 0
	s_setprio 1
	v_mfma_f32_16x16x32_bf16 v[118:121], v[146:149], v[162:165], v[118:121]
	v_mfma_f32_16x16x32_bf16 v[114:117], v[154:157], v[162:165], v[114:117]
	v_mfma_f32_16x16x32_bf16 v[102:105], v[146:149], v[170:173], v[102:105]
	v_mfma_f32_16x16x32_bf16 v[98:101], v[154:157], v[170:173], v[98:101]
	v_mfma_f32_16x16x32_bf16 v[86:89], v[146:149], v[178:181], v[86:89]
	v_mfma_f32_16x16x32_bf16 v[82:85], v[154:157], v[178:181], v[82:85]
	v_mfma_f32_16x16x32_bf16 v[70:73], v[146:149], v[186:189], v[70:73]
	v_mfma_f32_16x16x32_bf16 v[66:69], v[154:157], v[186:189], v[66:69]
	v_mfma_f32_16x16x32_bf16 v[118:121], v[150:153], v[166:169], v[118:121]
	v_mfma_f32_16x16x32_bf16 v[114:117], v[158:161], v[166:169], v[114:117]
	v_mfma_f32_16x16x32_bf16 v[102:105], v[150:153], v[174:177], v[102:105]
	v_mfma_f32_16x16x32_bf16 v[98:101], v[158:161], v[174:177], v[98:101]
	v_mfma_f32_16x16x32_bf16 v[86:89], v[150:153], v[182:185], v[86:89]
	v_mfma_f32_16x16x32_bf16 v[82:85], v[158:161], v[182:185], v[82:85]
	v_mfma_f32_16x16x32_bf16 v[70:73], v[150:153], v[190:193], v[70:73]
	v_mfma_f32_16x16x32_bf16 v[66:69], v[158:161], v[190:193], v[66:69]
	s_setprio 0
	s_barrier
	s_add_i32 s87, s87, s95
	v_lshl_add_u64 v[202:203], s[80:81], 0, v[194:195]
	s_mov_b32 m0, s87
	ds_read_b128 v[162:165], v233 offset:16384
	ds_read_b128 v[166:169], v233 offset:17408
	ds_read_b128 v[170:173], v233 offset:18432
	ds_read_b128 v[174:177], v233 offset:19456
	ds_read_b128 v[178:181], v233 offset:20480
	ds_read_b128 v[182:185], v233 offset:21504
	ds_read_b128 v[186:189], v233 offset:22528
	ds_read_b128 v[190:193], v233 offset:23552
	global_load_lds_dwordx4 v[202:203], off
	s_add_i32 m0, s87, 0x2000
	s_add_u32 vcc_lo, s80, 0x80000
	v_lshl_add_u64 v[204:205], s[80:81], 0, v[196:197]
	s_addc_u32 vcc_hi, s81, 0
	s_add_i32 s87, s92, s95
	global_load_lds_dwordx4 v[204:205], off
	v_lshl_add_u64 v[206:207], vcc, 0, v[194:195]
	s_mov_b32 m0, s87
	v_lshl_add_u64 v[214:215], s[82:83], 0, v[196:197]
	global_load_lds_dwordx4 v[206:207], off
	v_lshl_add_u64 v[206:207], vcc, 0, v[196:197]
	s_add_i32 m0, s87, 0x2000
	s_nop 0
	global_load_lds_dwordx4 v[206:207], off
	v_lshl_add_u64 v[206:207], s[82:83], 0, v[194:195]
	s_mov_b32 m0, s61
	s_nop 0
	global_load_lds_dwordx4 v[206:207], off
	s_mov_b32 m0, s44
	s_nop 0
	global_load_lds_dwordx4 v[214:215], off
	s_waitcnt vmcnt(24)
	s_waitcnt lgkmcnt(0)
	s_barrier
	s_setprio 1
	s_waitcnt lgkmcnt(0)
	v_mfma_f32_16x16x32_bf16 v[62:65], v[126:129], v[162:165], v[62:65]
	v_mfma_f32_16x16x32_bf16 v[58:61], v[138:141], v[162:165], v[58:61]
	v_mfma_f32_16x16x32_bf16 v[46:49], v[126:129], v[170:173], v[46:49]
	v_mfma_f32_16x16x32_bf16 v[42:45], v[138:141], v[170:173], v[42:45]
	v_mfma_f32_16x16x32_bf16 v[30:33], v[126:129], v[178:181], v[30:33]
	v_mfma_f32_16x16x32_bf16 v[26:29], v[138:141], v[178:181], v[26:29]
	v_mfma_f32_16x16x32_bf16 v[14:17], v[126:129], v[186:189], v[14:17]
	v_mfma_f32_16x16x32_bf16 v[10:13], v[138:141], v[186:189], v[10:13]
	v_mfma_f32_16x16x32_bf16 v[62:65], v[134:137], v[166:169], v[62:65]
	v_mfma_f32_16x16x32_bf16 v[58:61], v[142:145], v[166:169], v[58:61]
	v_mfma_f32_16x16x32_bf16 v[46:49], v[134:137], v[174:177], v[46:49]
	v_mfma_f32_16x16x32_bf16 v[42:45], v[142:145], v[174:177], v[42:45]
	v_mfma_f32_16x16x32_bf16 v[30:33], v[134:137], v[182:185], v[30:33]
	v_mfma_f32_16x16x32_bf16 v[26:29], v[142:145], v[182:185], v[26:29]
	v_mfma_f32_16x16x32_bf16 v[14:17], v[134:137], v[190:193], v[14:17]
	v_mfma_f32_16x16x32_bf16 v[10:13], v[142:145], v[190:193], v[10:13]
	s_setprio 0
	s_setprio 1
	v_mfma_f32_16x16x32_bf16 v[54:57], v[146:149], v[162:165], v[54:57]
	v_mfma_f32_16x16x32_bf16 v[50:53], v[154:157], v[162:165], v[50:53]
	v_mfma_f32_16x16x32_bf16 v[38:41], v[146:149], v[170:173], v[38:41]
	v_mfma_f32_16x16x32_bf16 v[34:37], v[154:157], v[170:173], v[34:37]
	v_mfma_f32_16x16x32_bf16 v[22:25], v[146:149], v[178:181], v[22:25]
	v_mfma_f32_16x16x32_bf16 v[18:21], v[154:157], v[178:181], v[18:21]
	v_mfma_f32_16x16x32_bf16 v[6:9], v[146:149], v[186:189], v[6:9]
	v_mfma_f32_16x16x32_bf16 v[2:5], v[154:157], v[186:189], v[2:5]
	v_mfma_f32_16x16x32_bf16 v[54:57], v[150:153], v[166:169], v[54:57]
	v_mfma_f32_16x16x32_bf16 v[50:53], v[158:161], v[166:169], v[50:53]
	v_mfma_f32_16x16x32_bf16 v[38:41], v[150:153], v[174:177], v[38:41]
	v_mfma_f32_16x16x32_bf16 v[34:37], v[158:161], v[174:177], v[34:37]
	v_mfma_f32_16x16x32_bf16 v[22:25], v[150:153], v[182:185], v[22:25]
	v_mfma_f32_16x16x32_bf16 v[18:21], v[158:161], v[182:185], v[18:21]
	v_mfma_f32_16x16x32_bf16 v[6:9], v[150:153], v[190:193], v[6:9]
	v_mfma_f32_16x16x32_bf16 v[2:5], v[158:161], v[190:193], v[2:5]
	s_setprio 0
	s_barrier
	s_add_i32 s87, 0, 0x18000
	s_add_i32 s92, 0, 0x1c000
	v_add_u32_e32 v142, s87, v228
	v_add_u32_e32 v158, s92, v228
	ds_read_b128 v[126:129], v142
	ds_read_b128 v[134:137], v142 offset:1024
	ds_read_b128 v[138:141], v142 offset:2048
	ds_read_b128 v[142:145], v142 offset:3072
	ds_read_b128 v[146:149], v158
	ds_read_b128 v[150:153], v158 offset:1024
	ds_read_b128 v[154:157], v158 offset:2048
	ds_read_b128 v[158:161], v158 offset:3072
	s_add_u32 s82, s82, 0x80000
	s_addc_u32 s83, s83, 0
	s_mov_b32 m0, s45
	v_lshl_add_u64 v[216:217], s[82:83], 0, v[194:195]
	ds_read_b128 v[162:165], v233 offset:32768
	ds_read_b128 v[166:169], v233 offset:33792
	ds_read_b128 v[170:173], v233 offset:34816
	ds_read_b128 v[174:177], v233 offset:35840
	ds_read_b128 v[178:181], v233 offset:36864
	ds_read_b128 v[182:185], v233 offset:37888
	ds_read_b128 v[186:189], v233 offset:38912
	ds_read_b128 v[190:193], v233 offset:39936
	global_load_lds_dwordx4 v[216:217], off
	v_lshl_add_u64 v[216:217], s[82:83], 0, v[196:197]
	s_mov_b32 m0, s88
	s_nop 0
	global_load_lds_dwordx4 v[216:217], off
	s_waitcnt vmcnt(8)
	s_waitcnt lgkmcnt(0)
	s_barrier
	s_setprio 1
	s_waitcnt lgkmcnt(0)
	v_mfma_f32_16x16x32_bf16 v[130:133], v[126:129], v[162:165], v[130:133]
	v_mfma_f32_16x16x32_bf16 v[122:125], v[138:141], v[162:165], v[122:125]
	v_mfma_f32_16x16x32_bf16 v[110:113], v[126:129], v[170:173], v[110:113]
	v_mfma_f32_16x16x32_bf16 v[106:109], v[138:141], v[170:173], v[106:109]
	v_mfma_f32_16x16x32_bf16 v[94:97], v[126:129], v[178:181], v[94:97]
	v_mfma_f32_16x16x32_bf16 v[90:93], v[138:141], v[178:181], v[90:93]
	v_mfma_f32_16x16x32_bf16 v[78:81], v[126:129], v[186:189], v[78:81]
	v_mfma_f32_16x16x32_bf16 v[74:77], v[138:141], v[186:189], v[74:77]
	v_mfma_f32_16x16x32_bf16 v[130:133], v[134:137], v[166:169], v[130:133]
	v_mfma_f32_16x16x32_bf16 v[122:125], v[142:145], v[166:169], v[122:125]
	v_mfma_f32_16x16x32_bf16 v[110:113], v[134:137], v[174:177], v[110:113]
	v_mfma_f32_16x16x32_bf16 v[106:109], v[142:145], v[174:177], v[106:109]
	v_mfma_f32_16x16x32_bf16 v[94:97], v[134:137], v[182:185], v[94:97]
	v_mfma_f32_16x16x32_bf16 v[90:93], v[142:145], v[182:185], v[90:93]
	v_mfma_f32_16x16x32_bf16 v[78:81], v[134:137], v[190:193], v[78:81]
	v_mfma_f32_16x16x32_bf16 v[74:77], v[142:145], v[190:193], v[74:77]
	s_setprio 0
	s_setprio 1
	v_mfma_f32_16x16x32_bf16 v[118:121], v[146:149], v[162:165], v[118:121]
	v_mfma_f32_16x16x32_bf16 v[114:117], v[154:157], v[162:165], v[114:117]
	v_mfma_f32_16x16x32_bf16 v[102:105], v[146:149], v[170:173], v[102:105]
	v_mfma_f32_16x16x32_bf16 v[98:101], v[154:157], v[170:173], v[98:101]
	v_mfma_f32_16x16x32_bf16 v[86:89], v[146:149], v[178:181], v[86:89]
	v_mfma_f32_16x16x32_bf16 v[82:85], v[154:157], v[178:181], v[82:85]
	v_mfma_f32_16x16x32_bf16 v[70:73], v[146:149], v[186:189], v[70:73]
	v_mfma_f32_16x16x32_bf16 v[66:69], v[154:157], v[186:189], v[66:69]
	v_mfma_f32_16x16x32_bf16 v[118:121], v[150:153], v[166:169], v[118:121]
	v_mfma_f32_16x16x32_bf16 v[114:117], v[158:161], v[166:169], v[114:117]
	v_mfma_f32_16x16x32_bf16 v[102:105], v[150:153], v[174:177], v[102:105]
	v_mfma_f32_16x16x32_bf16 v[98:101], v[158:161], v[174:177], v[98:101]
	v_mfma_f32_16x16x32_bf16 v[86:89], v[150:153], v[182:185], v[86:89]
	v_mfma_f32_16x16x32_bf16 v[82:85], v[158:161], v[182:185], v[82:85]
	v_mfma_f32_16x16x32_bf16 v[70:73], v[150:153], v[190:193], v[70:73]
	v_mfma_f32_16x16x32_bf16 v[66:69], v[158:161], v[190:193], v[66:69]
	s_setprio 0
	s_barrier
	s_add_i32 s82, s87, s95
	v_lshl_add_u64 v[202:203], v[202:203], 0, s[54:55]
	s_mov_b32 m0, s82
	ds_read_b128 v[162:165], v233 offset:49152
	ds_read_b128 v[166:169], v233 offset:50176
	ds_read_b128 v[170:173], v233 offset:51200
	ds_read_b128 v[174:177], v233 offset:52224
	ds_read_b128 v[178:181], v233 offset:53248
	ds_read_b128 v[182:185], v233 offset:54272
	ds_read_b128 v[186:189], v233 offset:55296
	ds_read_b128 v[190:193], v233 offset:56320
	global_load_lds_dwordx4 v[202:203], off
	s_add_i32 m0, s82, 0x2000
	s_add_u32 s80, s80, 0x80080
	v_lshl_add_u64 v[202:203], v[204:205], 0, s[54:55]
	s_addc_u32 s81, s81, 0
	s_add_i32 s82, s92, s95
	global_load_lds_dwordx4 v[202:203], off
	v_lshl_add_u64 v[202:203], s[80:81], 0, v[194:195]
	s_mov_b32 m0, s82
	s_nop 0
	global_load_lds_dwordx4 v[202:203], off
	v_lshl_add_u64 v[202:203], s[80:81], 0, v[196:197]
	s_add_i32 m0, s82, 0x2000
	s_nop 0
	global_load_lds_dwordx4 v[202:203], off
	v_lshl_add_u64 v[202:203], v[206:207], 0, s[54:55]
	s_mov_b32 m0, s48
	s_nop 0
	global_load_lds_dwordx4 v[202:203], off
	v_lshl_add_u64 v[202:203], v[214:215], 0, s[54:55]
	s_mov_b32 m0, s49
	s_nop 0
	global_load_lds_dwordx4 v[202:203], off
	s_waitcnt vmcnt(8)
	s_waitcnt lgkmcnt(0)
	s_barrier
	s_setprio 1
	s_waitcnt lgkmcnt(0)
	v_mfma_f32_16x16x32_bf16 v[62:65], v[126:129], v[162:165], v[62:65]
	v_mfma_f32_16x16x32_bf16 v[58:61], v[138:141], v[162:165], v[58:61]
	v_mfma_f32_16x16x32_bf16 v[46:49], v[126:129], v[170:173], v[46:49]
	v_mfma_f32_16x16x32_bf16 v[42:45], v[138:141], v[170:173], v[42:45]
	v_mfma_f32_16x16x32_bf16 v[30:33], v[126:129], v[178:181], v[30:33]
	v_mfma_f32_16x16x32_bf16 v[26:29], v[138:141], v[178:181], v[26:29]
	v_mfma_f32_16x16x32_bf16 v[14:17], v[126:129], v[186:189], v[14:17]
	v_mfma_f32_16x16x32_bf16 v[10:13], v[138:141], v[186:189], v[10:13]
	v_mfma_f32_16x16x32_bf16 v[62:65], v[134:137], v[166:169], v[62:65]
	v_mfma_f32_16x16x32_bf16 v[58:61], v[142:145], v[166:169], v[58:61]
	v_mfma_f32_16x16x32_bf16 v[46:49], v[134:137], v[174:177], v[46:49]
	v_mfma_f32_16x16x32_bf16 v[42:45], v[142:145], v[174:177], v[42:45]
	v_mfma_f32_16x16x32_bf16 v[30:33], v[134:137], v[182:185], v[30:33]
	v_mfma_f32_16x16x32_bf16 v[26:29], v[142:145], v[182:185], v[26:29]
	v_mfma_f32_16x16x32_bf16 v[14:17], v[134:137], v[190:193], v[14:17]
	v_mfma_f32_16x16x32_bf16 v[10:13], v[142:145], v[190:193], v[10:13]
	s_setprio 0
	s_setprio 1
	v_mfma_f32_16x16x32_bf16 v[54:57], v[146:149], v[162:165], v[54:57]
	v_mfma_f32_16x16x32_bf16 v[50:53], v[154:157], v[162:165], v[50:53]
	v_mfma_f32_16x16x32_bf16 v[38:41], v[146:149], v[170:173], v[38:41]
	v_mfma_f32_16x16x32_bf16 v[34:37], v[154:157], v[170:173], v[34:37]
	v_mfma_f32_16x16x32_bf16 v[22:25], v[146:149], v[178:181], v[22:25]
	v_mfma_f32_16x16x32_bf16 v[18:21], v[154:157], v[178:181], v[18:21]
	v_mfma_f32_16x16x32_bf16 v[6:9], v[146:149], v[186:189], v[6:9]
	v_mfma_f32_16x16x32_bf16 v[2:5], v[154:157], v[186:189], v[2:5]
	v_mfma_f32_16x16x32_bf16 v[54:57], v[150:153], v[166:169], v[54:57]
	v_mfma_f32_16x16x32_bf16 v[50:53], v[158:161], v[166:169], v[50:53]
	v_mfma_f32_16x16x32_bf16 v[38:41], v[150:153], v[174:177], v[38:41]
	v_mfma_f32_16x16x32_bf16 v[34:37], v[158:161], v[174:177], v[34:37]
	v_mfma_f32_16x16x32_bf16 v[22:25], v[150:153], v[182:185], v[22:25]
	v_mfma_f32_16x16x32_bf16 v[18:21], v[158:161], v[182:185], v[18:21]
	v_mfma_f32_16x16x32_bf16 v[6:9], v[150:153], v[190:193], v[6:9]
	v_mfma_f32_16x16x32_bf16 v[2:5], v[158:161], v[190:193], v[2:5]
	s_setprio 0
	s_barrier
	s_add_i32 s86, s86, 2
	s_add_u32 s84, s84, 0x100
	s_addc_u32 s85, s85, 0
	s_add_u32 s8, s8, 0x100
	s_addc_u32 s9, s9, 0
	s_cmp_gt_u32 s86, 29
	s_cbranch_scc1 .Lpeel_exit_G1

.Lpeel_exit_G1:
	s_mov_b32 s99, 1
	s_and_b64 vcc, exec, s[28:29]
	s_cbranch_vccz .LBB0_608
	s_barrier

.LBB0_1050:
	s_andn2_b64 vcc, exec, s[4:5]
	s_cbranch_vccnz .LBB0_1174
	s_mov_b32 s99, 0
	s_mov_b64 s[4:5], s[40:41]
	s_mov_b32 s37, s52
	s_mov_b64 s[6:7], s[42:43]
	s_mov_b32 s36, s63
	s_mov_b32 s8, s2
	s_add_u32 s34, s6, 0x5612000
	v_mbcnt_lo_u32_b32 v136, -1, 0
	v_mbcnt_hi_u32_b32 v136, -1, v136
	s_addc_u32 s35, s7, 0
	v_lshl_add_u32 v16, s8, 6, v136
	s_ashr_i32 s39, s36, 31
	s_ashr_i32 s66, s37, 31
	v_readfirstlane_b32 s38, v16
	s_cmpk_gt_i32 s37, 0x57f
	s_nop 0
	v_readfirstlane_b32 s5, v16
	s_cbranch_scc1 .LBB0_1067
	v_lshlrev_b32_e32 v0, 4, v16
	v_add_u32_e32 v2, 0x2000, v0
	v_ashrrev_i32_e32 v3, 31, v2
	v_lshrrev_b32_e32 v3, 22, v3
	v_add_u32_e32 v3, v2, v3
	v_ashrrev_i32_e32 v10, 10, v3
	v_mul_i32_i24_e32 v4, 0x400, v10
	v_sub_u32_e32 v2, v2, v4
	v_lshrrev_b32_e32 v4, 4, v2
	v_bitop3_b32 v2, v4, v2, 32 bitop3:0x6c
	s_add_u32 s67, s6, 0x19e12000
	s_mul_i32 s8, s56, 0x1600000
	s_mov_b32 s9, s50
	v_ashrrev_i32_e32 v4, 31, v2
	s_addc_u32 s78, s7, 0
	s_lshl_b64 s[8:9], s[8:9], 1
	v_lshrrev_b32_e32 v4, 26, v4
	s_add_u32 s79, s34, s8
	v_add_u32_e32 v4, v2, v4
	s_addc_u32 s80, s35, s9
	v_ashrrev_i32_e32 v11, 6, v4
	v_and_b32_e32 v4, 0xc0, v4
	s_ashr_i32 s4, s37, 31
	v_sub_u32_e32 v2, v2, v4
	s_lshr_b32 s4, s4, 29
	v_lshlrev_b32_e32 v3, 5, v10
	v_ashrrev_i16_sdwa v2, v224, sext(v2) dst_sel:DWORD dst_unused:UNUSED_PAD src0_sel:DWORD src1_sel:BYTE_0
	s_add_i32 s4, s37, s4
	s_ashr_i32 s14, s5, 6
	v_and_b32_e32 v3, 32, v3
	v_bfe_i32 v12, v2, 0, 16
	s_ashr_i32 s8, s4, 3
	s_and_b32 s4, s4, -8
	s_ashr_i32 s15, s5, 8
	s_lshl_b32 s81, s14, 10
	v_add_u32_e32 v2, v3, v12
	v_lshlrev_b32_e32 v3, 3, v10
	s_sub_i32 s4, s37, s4
	v_and_b32_e32 v3, 0xffff0, v3
	s_cmp_lt_i32 s4, 0
	v_add_lshl_u32 v3, v11, v3, 12
	s_cselect_b32 s9, s3, 0xb0
	v_lshl_add_u32 v130, v2, 1, v3
	v_bfe_i32 v3, v16, 27, 1
	s_mul_i32 s4, s4, s9
	v_lshrrev_b32_e32 v3, 22, v3
	s_add_i32 s4, s4, s8
	v_add_u32_e32 v3, v0, v3
	s_mul_hi_i32 s8, s4, 0x2e8ba2e9
	v_and_b32_e32 v3, 0xfffffc00, v3
	s_lshr_b32 s9, s8, 31
	s_ashr_i32 s8, s8, 6
	v_sub_u32_e32 v0, v0, v3
	s_add_i32 s8, s8, s9
	v_lshrrev_b32_e32 v3, 4, v0
	s_lshl_b32 s9, s8, 3
	s_mulk_i32 s8, 0x160
	v_bitop3_b32 v0, v3, v0, 32 bitop3:0x6c
	s_sub_i32 s8, s4, s8
	v_ashrrev_i32_e32 v3, 31, v0
	s_bfe_u32 s4, s8, 0x3001c
	v_ashrrev_i32_e32 v2, 31, v16
	v_lshrrev_b32_e32 v3, 26, v3
	s_waitcnt lgkmcnt(0)
	s_add_i32 s10, s8, s4
	v_lshrrev_b32_e32 v2, 26, v2
	v_add_u32_e32 v3, v0, v3
	s_sext_i32_i16 s4, s10
	s_and_b32 s10, s10, 0xfff8
	v_add_u32_e32 v2, v16, v2
	v_ashrrev_i32_e32 v14, 6, v3
	v_and_b32_e32 v3, 0xc0, v3
	s_sub_i32 s8, s8, s10
	v_ashrrev_i32_e32 v13, 6, v2
	v_sub_u32_e32 v0, v0, v3
	s_sext_i32_i16 s8, s8
	v_lshlrev_b32_e32 v2, 5, v13
	v_ashrrev_i16_sdwa v0, v224, sext(v0) dst_sel:DWORD dst_unused:UNUSED_PAD src0_sel:DWORD src1_sel:BYTE_0
	s_lshr_b32 s4, s4, 3
	s_add_i32 s24, s9, s8
	v_and_b32_e32 v2, 32, v2
	v_bfe_i32 v15, v0, 0, 16
	s_ashr_i32 s25, s24, 31
	s_bfe_i64 s[10:11], s[4:5], 0x100000
	v_add_u32_e32 v0, v2, v15
	v_lshlrev_b32_e32 v2, 3, v13
	s_lshl_b64 s[8:9], s[24:25], 20
	s_lshl_b64 s[10:11], s[10:11], 20
	v_and_b32_e32 v2, 0xffff0, v2
	s_add_u32 s26, s79, s10
	v_add_lshl_u32 v2, v14, v2, 12
	s_addc_u32 s27, s80, s11
	s_add_i32 s82, s81, 0
	v_lshl_add_u32 v0, v0, 1, v2
	s_add_i32 m0, s82, 0x10000
	v_mov_b32_e32 v131, v1
	global_load_lds_dwordx4 v0, s[26:27]
	s_add_i32 m0, s82, 0x12000
	s_add_u32 s10, s26, 0x80000
	global_load_lds_dwordx4 v130, s[26:27]
	s_addc_u32 s11, s27, 0
	s_add_i32 m0, s82, 0x14000
	v_lshl_add_u64 v[8:9], s[26:27], 0, v[0:1]
	global_load_lds_dwordx4 v0, s[10:11]
	s_add_i32 m0, s82, 0x16000
	s_add_u32 s28, s67, s8
	s_addc_u32 s29, s78, s9
	s_add_i32 s68, s82, 0x2000
	global_load_lds_dwordx4 v130, s[10:11]
	s_mov_b32 m0, s82
	s_add_u32 s8, s28, 0x80000
	global_load_lds_dwordx4 v0, s[28:29]
	s_mov_b32 m0, s68
	s_addc_u32 s9, s29, 0
	s_add_i32 s69, s82, 0x4000
	global_load_lds_dwordx4 v130, s[28:29]
	s_mov_b32 m0, s69
	s_add_i32 s70, s82, 0x6000
	global_load_lds_dwordx4 v0, s[8:9]
	s_mov_b32 m0, s70
	s_cmp_eq_u32 s15, 1
	global_load_lds_dwordx4 v130, s[8:9]
	v_lshl_add_u64 v[6:7], s[26:27], 0, v[130:131]
	v_lshl_add_u64 v[2:3], s[28:29], 0, v[0:1]
	s_cselect_b64 s[8:9], -1, 0
	s_cmp_lg_u32 s15, 1
	v_lshl_add_u64 v[4:5], s[28:29], 0, v[130:131]
	s_cbranch_scc1 .LBB0_1054
	s_barrier

.LBB0_1059:
	s_ashr_i32 s19, s18, 31
	s_lshl_b64 s[20:21], s[18:19], 20
	s_add_u32 s20, s67, s20
	s_addc_u32 s21, s78, s21
	s_and_b64 s[22:23], s[4:5], exec
	s_cselect_b32 s19, s21, s29
	s_cselect_b32 s33, s20, s28
	s_ashr_i32 s17, s16, 31
	s_lshl_b64 s[22:23], s[16:17], 20
	s_add_u32 s22, s79, s22
	s_addc_u32 s23, s80, s23
	s_and_b64 s[30:31], s[4:5], exec
	s_cselect_b32 s17, s23, s27
	s_cselect_b32 s44, s22, s26
	s_add_u32 s45, s26, 0x100
	s_addc_u32 s48, s27, 0
	s_add_u32 s26, s28, 0x80080
	v_mov_b32_e32 v2, 0
	s_addc_u32 s27, s29, 0
	s_mov_b32 s49, -2
	v_mov_b32_e32 v3, v2
	v_mov_b32_e32 v4, v2
	v_mov_b32_e32 v5, v2
	v_mov_b32_e32 v10, v2
	v_mov_b32_e32 v11, v2
	v_mov_b32_e32 v12, v2
	v_mov_b32_e32 v13, v2
	v_mov_b32_e32 v18, v2
	v_mov_b32_e32 v19, v2
	v_mov_b32_e32 v20, v2
	v_mov_b32_e32 v21, v2
	v_mov_b32_e32 v26, v2
	v_mov_b32_e32 v27, v2
	v_mov_b32_e32 v28, v2
	v_mov_b32_e32 v29, v2
	v_mov_b32_e32 v34, v2
	v_mov_b32_e32 v35, v2
	v_mov_b32_e32 v36, v2
	v_mov_b32_e32 v37, v2
	v_mov_b32_e32 v42, v2
	v_mov_b32_e32 v43, v2
	v_mov_b32_e32 v44, v2
	v_mov_b32_e32 v45, v2
	v_mov_b32_e32 v50, v2
	v_mov_b32_e32 v51, v2
	v_mov_b32_e32 v52, v2
	v_mov_b32_e32 v53, v2
	v_mov_b32_e32 v58, v2
	v_mov_b32_e32 v59, v2
	v_mov_b32_e32 v60, v2
	v_mov_b32_e32 v61, v2
	v_mov_b32_e32 v6, v2
	v_mov_b32_e32 v7, v2
	v_mov_b32_e32 v8, v2
	v_mov_b32_e32 v9, v2
	v_mov_b32_e32 v14, v2
	v_mov_b32_e32 v15, v2
	v_mov_b32_e32 v16, v2
	v_mov_b32_e32 v17, v2
	v_mov_b32_e32 v22, v2
	v_mov_b32_e32 v23, v2
	v_mov_b32_e32 v24, v2
	v_mov_b32_e32 v25, v2
	v_mov_b32_e32 v30, v2
	v_mov_b32_e32 v31, v2
	v_mov_b32_e32 v32, v2
	v_mov_b32_e32 v33, v2
	v_mov_b32_e32 v38, v2
	v_mov_b32_e32 v39, v2
	v_mov_b32_e32 v40, v2
	v_mov_b32_e32 v41, v2
	v_mov_b32_e32 v46, v2
	v_mov_b32_e32 v47, v2
	v_mov_b32_e32 v48, v2
	v_mov_b32_e32 v49, v2
	v_mov_b32_e32 v54, v2
	v_mov_b32_e32 v55, v2
	v_mov_b32_e32 v56, v2
	v_mov_b32_e32 v57, v2
	v_mov_b32_e32 v62, v2
	v_mov_b32_e32 v63, v2
	v_mov_b32_e32 v64, v2
	v_mov_b32_e32 v65, v2
	v_mov_b32_e32 v66, v2
	v_mov_b32_e32 v67, v2
	v_mov_b32_e32 v68, v2
	v_mov_b32_e32 v69, v2
	v_mov_b32_e32 v74, v2
	v_mov_b32_e32 v75, v2
	v_mov_b32_e32 v76, v2
	v_mov_b32_e32 v77, v2
	v_mov_b32_e32 v82, v2
	v_mov_b32_e32 v83, v2
	v_mov_b32_e32 v84, v2
	v_mov_b32_e32 v85, v2
	v_mov_b32_e32 v90, v2
	v_mov_b32_e32 v91, v2
	v_mov_b32_e32 v92, v2
	v_mov_b32_e32 v93, v2
	v_mov_b32_e32 v98, v2
	v_mov_b32_e32 v99, v2
	v_mov_b32_e32 v100, v2
	v_mov_b32_e32 v101, v2
	v_mov_b32_e32 v106, v2
	v_mov_b32_e32 v107, v2
	v_mov_b32_e32 v108, v2
	v_mov_b32_e32 v109, v2
	v_mov_b32_e32 v114, v2
	v_mov_b32_e32 v115, v2
	v_mov_b32_e32 v116, v2
	v_mov_b32_e32 v117, v2
	v_mov_b32_e32 v122, v2
	v_mov_b32_e32 v123, v2
	v_mov_b32_e32 v124, v2
	v_mov_b32_e32 v125, v2
	v_mov_b32_e32 v70, v2
	v_mov_b32_e32 v71, v2
	v_mov_b32_e32 v72, v2
	v_mov_b32_e32 v73, v2
	v_mov_b32_e32 v78, v2
	v_mov_b32_e32 v79, v2
	v_mov_b32_e32 v80, v2
	v_mov_b32_e32 v81, v2
	v_mov_b32_e32 v86, v2
	v_mov_b32_e32 v87, v2
	v_mov_b32_e32 v88, v2
	v_mov_b32_e32 v89, v2
	v_mov_b32_e32 v94, v2
	v_mov_b32_e32 v95, v2
	v_mov_b32_e32 v96, v2
	v_mov_b32_e32 v97, v2
	v_mov_b32_e32 v102, v2
	v_mov_b32_e32 v103, v2
	v_mov_b32_e32 v104, v2
	v_mov_b32_e32 v105, v2
	v_mov_b32_e32 v110, v2
	v_mov_b32_e32 v111, v2
	v_mov_b32_e32 v112, v2
	v_mov_b32_e32 v113, v2
	v_mov_b32_e32 v118, v2
	v_mov_b32_e32 v119, v2
	v_mov_b32_e32 v120, v2
	v_mov_b32_e32 v121, v2
	v_mov_b32_e32 v126, v2
	v_mov_b32_e32 v127, v2
	v_mov_b32_e32 v128, v2
	v_mov_b32_e32 v129, v2
	s_cmp_eq_u32 s99, 0
	s_cbranch_scc1 .LBB0_1060
.Lpeel_G3:
	s_add_u32 s28, s26, 0xfff80080
	s_addc_u32 s29, s27, -1
	s_add_i32 s61, 0, 0x10000
	s_cmp_eq_u32 s49, 28
	s_cselect_b32 s31, s19, s29
	s_cselect_b32 s30, s33, s28
	v_add_u32_e32 v141, s61, v138
	s_cselect_b32 s29, s17, s48
	s_cselect_b32 s28, s44, s45
	s_add_i32 s73, 0, 0x14000
	ds_read_b128 v[142:145], v141
	ds_read_b128 v[146:149], v141 offset:1024
	ds_read_b128 v[150:153], v141 offset:2048
	ds_read_b128 v[154:157], v141 offset:3072
	v_add_u32_e32 v141, s73, v138
	ds_read_b128 v[158:161], v141
	ds_read_b128 v[162:165], v141 offset:1024
	ds_read_b128 v[166:169], v141 offset:2048
	ds_read_b128 v[170:173], v141 offset:3072
	v_lshl_add_u64 v[206:207], s[26:27], 0, v[134:135]
	s_add_i32 m0, s82, 0xc000
	ds_read_b128 v[174:177], v140
	ds_read_b128 v[178:181], v140 offset:1024
	ds_read_b128 v[182:185], v140 offset:2048
	ds_read_b128 v[186:189], v140 offset:3072
	ds_read_b128 v[190:193], v140 offset:4096
	ds_read_b128 v[194:197], v140 offset:5120
	ds_read_b128 v[198:201], v140 offset:6144
	ds_read_b128 v[202:205], v140 offset:7168
	global_load_lds_dwordx4 v[206:207], off
	v_lshl_add_u64 v[206:207], s[26:27], 0, v[132:133]
	s_add_i32 m0, s82, 0xe000
	s_nop 0
	global_load_lds_dwordx4 v[206:207], off
	s_waitcnt vmcnt(16)
	s_waitcnt lgkmcnt(0)
	s_barrier
	s_setprio 1
	s_waitcnt lgkmcnt(0)
	v_mfma_f32_16x16x32_bf16 v[126:129], v[142:145], v[174:177], v[126:129]
	v_mfma_f32_16x16x32_bf16 v[118:121], v[150:153], v[174:177], v[118:121]
	v_mfma_f32_16x16x32_bf16 v[110:113], v[142:145], v[182:185], v[110:113]
	v_mfma_f32_16x16x32_bf16 v[102:105], v[150:153], v[182:185], v[102:105]
	v_mfma_f32_16x16x32_bf16 v[94:97], v[142:145], v[190:193], v[94:97]
	v_mfma_f32_16x16x32_bf16 v[86:89], v[150:153], v[190:193], v[86:89]
	v_mfma_f32_16x16x32_bf16 v[78:81], v[142:145], v[198:201], v[78:81]
	v_mfma_f32_16x16x32_bf16 v[70:73], v[150:153], v[198:201], v[70:73]
	v_mfma_f32_16x16x32_bf16 v[126:129], v[146:149], v[178:181], v[126:129]
	v_mfma_f32_16x16x32_bf16 v[118:121], v[154:157], v[178:181], v[118:121]
	v_mfma_f32_16x16x32_bf16 v[110:113], v[146:149], v[186:189], v[110:113]
	v_mfma_f32_16x16x32_bf16 v[102:105], v[154:157], v[186:189], v[102:105]
	v_mfma_f32_16x16x32_bf16 v[94:97], v[146:149], v[194:197], v[94:97]
	v_mfma_f32_16x16x32_bf16 v[86:89], v[154:157], v[194:197], v[86:89]
	v_mfma_f32_16x16x32_bf16 v[78:81], v[146:149], v[202:205], v[78:81]
	v_mfma_f32_16x16x32_bf16 v[70:73], v[154:157], v[202:205], v[70:73]
	s_setprio 0
	s_setprio 1
	v_mfma_f32_16x16x32_bf16 v[122:125], v[158:161], v[174:177], v[122:125]
	v_mfma_f32_16x16x32_bf16 v[114:117], v[166:169], v[174:177], v[114:117]
	v_mfma_f32_16x16x32_bf16 v[106:109], v[158:161], v[182:185], v[106:109]
	v_mfma_f32_16x16x32_bf16 v[98:101], v[166:169], v[182:185], v[98:101]
	v_mfma_f32_16x16x32_bf16 v[90:93], v[158:161], v[190:193], v[90:93]
	v_mfma_f32_16x16x32_bf16 v[82:85], v[166:169], v[190:193], v[82:85]
	v_mfma_f32_16x16x32_bf16 v[74:77], v[158:161], v[198:201], v[74:77]
	v_mfma_f32_16x16x32_bf16 v[66:69], v[166:169], v[198:201], v[66:69]
	v_mfma_f32_16x16x32_bf16 v[122:125], v[162:165], v[178:181], v[122:125]
	v_mfma_f32_16x16x32_bf16 v[114:117], v[170:173], v[178:181], v[114:117]
	v_mfma_f32_16x16x32_bf16 v[106:109], v[162:165], v[186:189], v[106:109]
	v_mfma_f32_16x16x32_bf16 v[98:101], v[170:173], v[186:189], v[98:101]
	v_mfma_f32_16x16x32_bf16 v[90:93], v[162:165], v[194:197], v[90:93]
	v_mfma_f32_16x16x32_bf16 v[82:85], v[170:173], v[194:197], v[82:85]
	v_mfma_f32_16x16x32_bf16 v[74:77], v[162:165], v[202:205], v[74:77]
	v_mfma_f32_16x16x32_bf16 v[66:69], v[170:173], v[202:205], v[66:69]
	s_setprio 0
	s_barrier
	s_add_i32 s61, s61, s81
	v_lshl_add_u64 v[206:207], s[28:29], 0, v[0:1]
	s_mov_b32 m0, s61
	ds_read_b128 v[174:177], v140 offset:16384
	ds_read_b128 v[178:181], v140 offset:17408
	ds_read_b128 v[182:185], v140 offset:18432
	ds_read_b128 v[186:189], v140 offset:19456
	ds_read_b128 v[190:193], v140 offset:20480
	ds_read_b128 v[194:197], v140 offset:21504
	ds_read_b128 v[198:201], v140 offset:22528
	ds_read_b128 v[202:205], v140 offset:23552
	global_load_lds_dwordx4 v[206:207], off
	s_add_i32 m0, s61, 0x2000
	s_add_u32 s84, s28, 0x80000
	v_lshl_add_u64 v[208:209], s[28:29], 0, v[130:131]
	s_addc_u32 s85, s29, 0
	s_add_i32 s61, s73, s81
	global_load_lds_dwordx4 v[208:209], off
	v_lshl_add_u64 v[210:211], s[84:85], 0, v[0:1]
	s_mov_b32 m0, s61
	v_lshl_add_u64 v[212:213], s[30:31], 0, v[130:131]
	global_load_lds_dwordx4 v[210:211], off
	v_lshl_add_u64 v[210:211], s[84:85], 0, v[130:131]
	s_add_i32 m0, s61, 0x2000
	s_nop 0
	global_load_lds_dwordx4 v[210:211], off
	v_lshl_add_u64 v[210:211], s[30:31], 0, v[0:1]
	s_mov_b32 m0, s82
	s_nop 0
	global_load_lds_dwordx4 v[210:211], off
	s_mov_b32 m0, s68
	s_nop 0
	global_load_lds_dwordx4 v[212:213], off
	s_waitcnt vmcnt(16)
	s_waitcnt lgkmcnt(0)
	s_barrier
	s_setprio 1
	s_waitcnt lgkmcnt(0)
	v_mfma_f32_16x16x32_bf16 v[62:65], v[142:145], v[174:177], v[62:65]
	v_mfma_f32_16x16x32_bf16 v[54:57], v[150:153], v[174:177], v[54:57]
	v_mfma_f32_16x16x32_bf16 v[46:49], v[142:145], v[182:185], v[46:49]
	v_mfma_f32_16x16x32_bf16 v[38:41], v[150:153], v[182:185], v[38:41]
	v_mfma_f32_16x16x32_bf16 v[30:33], v[142:145], v[190:193], v[30:33]
	v_mfma_f32_16x16x32_bf16 v[22:25], v[150:153], v[190:193], v[22:25]
	v_mfma_f32_16x16x32_bf16 v[14:17], v[142:145], v[198:201], v[14:17]
	v_mfma_f32_16x16x32_bf16 v[6:9], v[150:153], v[198:201], v[6:9]
	v_mfma_f32_16x16x32_bf16 v[62:65], v[146:149], v[178:181], v[62:65]
	v_mfma_f32_16x16x32_bf16 v[54:57], v[154:157], v[178:181], v[54:57]
	v_mfma_f32_16x16x32_bf16 v[46:49], v[146:149], v[186:189], v[46:49]
	v_mfma_f32_16x16x32_bf16 v[38:41], v[154:157], v[186:189], v[38:41]
	v_mfma_f32_16x16x32_bf16 v[30:33], v[146:149], v[194:197], v[30:33]
	v_mfma_f32_16x16x32_bf16 v[22:25], v[154:157], v[194:197], v[22:25]
	v_mfma_f32_16x16x32_bf16 v[14:17], v[146:149], v[202:205], v[14:17]
	v_mfma_f32_16x16x32_bf16 v[6:9], v[154:157], v[202:205], v[6:9]
	s_setprio 0
	s_setprio 1
	v_mfma_f32_16x16x32_bf16 v[58:61], v[158:161], v[174:177], v[58:61]
	v_mfma_f32_16x16x32_bf16 v[50:53], v[166:169], v[174:177], v[50:53]
	v_mfma_f32_16x16x32_bf16 v[42:45], v[158:161], v[182:185], v[42:45]
	v_mfma_f32_16x16x32_bf16 v[34:37], v[166:169], v[182:185], v[34:37]
	v_mfma_f32_16x16x32_bf16 v[26:29], v[158:161], v[190:193], v[26:29]
	v_mfma_f32_16x16x32_bf16 v[18:21], v[166:169], v[190:193], v[18:21]
	v_mfma_f32_16x16x32_bf16 v[10:13], v[158:161], v[198:201], v[10:13]
	v_mfma_f32_16x16x32_bf16 v[2:5], v[166:169], v[198:201], v[2:5]
	v_mfma_f32_16x16x32_bf16 v[58:61], v[162:165], v[178:181], v[58:61]
	v_mfma_f32_16x16x32_bf16 v[50:53], v[170:173], v[178:181], v[50:53]
	v_mfma_f32_16x16x32_bf16 v[42:45], v[162:165], v[186:189], v[42:45]
	v_mfma_f32_16x16x32_bf16 v[34:37], v[170:173], v[186:189], v[34:37]
	v_mfma_f32_16x16x32_bf16 v[26:29], v[162:165], v[194:197], v[26:29]
	v_mfma_f32_16x16x32_bf16 v[18:21], v[170:173], v[194:197], v[18:21]
	v_mfma_f32_16x16x32_bf16 v[10:13], v[162:165], v[202:205], v[10:13]
	v_mfma_f32_16x16x32_bf16 v[2:5], v[170:173], v[202:205], v[2:5]
	s_setprio 0
	s_barrier
	s_add_i32 s61, 0, 0x18000
	v_add_u32_e32 v141, s61, v138
	s_add_i32 s73, 0, 0x1c000
	ds_read_b128 v[142:145], v141
	ds_read_b128 v[146:149], v141 offset:1024
	ds_read_b128 v[150:153], v141 offset:2048
	ds_read_b128 v[154:157], v141 offset:3072
	v_add_u32_e32 v141, s73, v138
	ds_read_b128 v[158:161], v141
	ds_read_b128 v[162:165], v141 offset:1024
	ds_read_b128 v[166:169], v141 offset:2048
	ds_read_b128 v[170:173], v141 offset:3072
	s_add_u32 s30, s30, 0x80000
	s_addc_u32 s31, s31, 0
	s_mov_b32 m0, s69
	v_lshl_add_u64 v[214:215], s[30:31], 0, v[0:1]
	ds_read_b128 v[174:177], v140 offset:32768
	ds_read_b128 v[178:181], v140 offset:33792
	ds_read_b128 v[182:185], v140 offset:34816
	ds_read_b128 v[186:189], v140 offset:35840
	ds_read_b128 v[190:193], v140 offset:36864
	ds_read_b128 v[194:197], v140 offset:37888
	ds_read_b128 v[198:201], v140 offset:38912
	ds_read_b128 v[202:205], v140 offset:39936
	global_load_lds_dwordx4 v[214:215], off
	v_lshl_add_u64 v[214:215], s[30:31], 0, v[130:131]
	s_mov_b32 m0, s70
	s_nop 0
	global_load_lds_dwordx4 v[214:215], off
	s_waitcnt vmcnt(8)
	s_waitcnt lgkmcnt(0)
	s_barrier
	s_setprio 1
	s_waitcnt lgkmcnt(0)
	v_mfma_f32_16x16x32_bf16 v[126:129], v[142:145], v[174:177], v[126:129]
	v_mfma_f32_16x16x32_bf16 v[118:121], v[150:153], v[174:177], v[118:121]
	v_mfma_f32_16x16x32_bf16 v[110:113], v[142:145], v[182:185], v[110:113]
	v_mfma_f32_16x16x32_bf16 v[102:105], v[150:153], v[182:185], v[102:105]
	v_mfma_f32_16x16x32_bf16 v[94:97], v[142:145], v[190:193], v[94:97]
	v_mfma_f32_16x16x32_bf16 v[86:89], v[150:153], v[190:193], v[86:89]
	v_mfma_f32_16x16x32_bf16 v[78:81], v[142:145], v[198:201], v[78:81]
	v_mfma_f32_16x16x32_bf16 v[70:73], v[150:153], v[198:201], v[70:73]
	v_mfma_f32_16x16x32_bf16 v[126:129], v[146:149], v[178:181], v[126:129]
	v_mfma_f32_16x16x32_bf16 v[118:121], v[154:157], v[178:181], v[118:121]
	v_mfma_f32_16x16x32_bf16 v[110:113], v[146:149], v[186:189], v[110:113]
	v_mfma_f32_16x16x32_bf16 v[102:105], v[154:157], v[186:189], v[102:105]
	v_mfma_f32_16x16x32_bf16 v[94:97], v[146:149], v[194:197], v[94:97]
	v_mfma_f32_16x16x32_bf16 v[86:89], v[154:157], v[194:197], v[86:89]
	v_mfma_f32_16x16x32_bf16 v[78:81], v[146:149], v[202:205], v[78:81]
	v_mfma_f32_16x16x32_bf16 v[70:73], v[154:157], v[202:205], v[70:73]
	s_setprio 0
	s_setprio 1
	v_mfma_f32_16x16x32_bf16 v[122:125], v[158:161], v[174:177], v[122:125]
	v_mfma_f32_16x16x32_bf16 v[114:117], v[166:169], v[174:177], v[114:117]
	v_mfma_f32_16x16x32_bf16 v[106:109], v[158:161], v[182:185], v[106:109]
	v_mfma_f32_16x16x32_bf16 v[98:101], v[166:169], v[182:185], v[98:101]
	v_mfma_f32_16x16x32_bf16 v[90:93], v[158:161], v[190:193], v[90:93]
	v_mfma_f32_16x16x32_bf16 v[82:85], v[166:169], v[190:193], v[82:85]
	v_mfma_f32_16x16x32_bf16 v[74:77], v[158:161], v[198:201], v[74:77]
	v_mfma_f32_16x16x32_bf16 v[66:69], v[166:169], v[198:201], v[66:69]
	v_mfma_f32_16x16x32_bf16 v[122:125], v[162:165], v[178:181], v[122:125]
	v_mfma_f32_16x16x32_bf16 v[114:117], v[170:173], v[178:181], v[114:117]
	v_mfma_f32_16x16x32_bf16 v[106:109], v[162:165], v[186:189], v[106:109]
	v_mfma_f32_16x16x32_bf16 v[98:101], v[170:173], v[186:189], v[98:101]
	v_mfma_f32_16x16x32_bf16 v[90:93], v[162:165], v[194:197], v[90:93]
	v_mfma_f32_16x16x32_bf16 v[82:85], v[170:173], v[194:197], v[82:85]
	v_mfma_f32_16x16x32_bf16 v[74:77], v[162:165], v[202:205], v[74:77]
	v_mfma_f32_16x16x32_bf16 v[66:69], v[170:173], v[202:205], v[66:69]
	s_setprio 0
	s_barrier
	s_add_i32 s30, s61, s81
	v_lshl_add_u64 v[206:207], v[206:207], 0, s[54:55]
	s_mov_b32 m0, s30
	ds_read_b128 v[174:177], v140 offset:49152
	ds_read_b128 v[178:181], v140 offset:50176
	ds_read_b128 v[182:185], v140 offset:51200
	ds_read_b128 v[186:189], v140 offset:52224
	ds_read_b128 v[190:193], v140 offset:53248
	ds_read_b128 v[194:197], v140 offset:54272
	ds_read_b128 v[198:201], v140 offset:55296
	ds_read_b128 v[202:205], v140 offset:56320
	global_load_lds_dwordx4 v[206:207], off
	s_add_i32 m0, s30, 0x2000
	s_add_u32 s28, s28, 0x80080
	v_lshl_add_u64 v[206:207], v[208:209], 0, s[54:55]
	s_addc_u32 s29, s29, 0
	s_add_i32 s30, s73, s81
	global_load_lds_dwordx4 v[206:207], off
	v_lshl_add_u64 v[206:207], s[28:29], 0, v[0:1]
	s_mov_b32 m0, s30
	s_nop 0
	global_load_lds_dwordx4 v[206:207], off
	v_lshl_add_u64 v[206:207], s[28:29], 0, v[130:131]
	s_add_i32 m0, s30, 0x2000
	s_nop 0
	global_load_lds_dwordx4 v[206:207], off
	v_lshl_add_u64 v[206:207], v[210:211], 0, s[54:55]
	s_mov_b32 m0, s71
	s_nop 0
	global_load_lds_dwordx4 v[206:207], off
	v_lshl_add_u64 v[206:207], v[212:213], 0, s[54:55]
	s_mov_b32 m0, s72
	s_nop 0
	global_load_lds_dwordx4 v[206:207], off
	s_waitcnt vmcnt(8)
	s_waitcnt lgkmcnt(0)
	s_barrier
	s_setprio 1
	s_waitcnt lgkmcnt(0)
	v_mfma_f32_16x16x32_bf16 v[62:65], v[142:145], v[174:177], v[62:65]
	v_mfma_f32_16x16x32_bf16 v[54:57], v[150:153], v[174:177], v[54:57]
	v_mfma_f32_16x16x32_bf16 v[46:49], v[142:145], v[182:185], v[46:49]
	v_mfma_f32_16x16x32_bf16 v[38:41], v[150:153], v[182:185], v[38:41]
	v_mfma_f32_16x16x32_bf16 v[30:33], v[142:145], v[190:193], v[30:33]
	v_mfma_f32_16x16x32_bf16 v[22:25], v[150:153], v[190:193], v[22:25]
	v_mfma_f32_16x16x32_bf16 v[14:17], v[142:145], v[198:201], v[14:17]
	v_mfma_f32_16x16x32_bf16 v[6:9], v[150:153], v[198:201], v[6:9]
	v_mfma_f32_16x16x32_bf16 v[62:65], v[146:149], v[178:181], v[62:65]
	v_mfma_f32_16x16x32_bf16 v[54:57], v[154:157], v[178:181], v[54:57]
	v_mfma_f32_16x16x32_bf16 v[46:49], v[146:149], v[186:189], v[46:49]
	v_mfma_f32_16x16x32_bf16 v[38:41], v[154:157], v[186:189], v[38:41]
	v_mfma_f32_16x16x32_bf16 v[30:33], v[146:149], v[194:197], v[30:33]
	v_mfma_f32_16x16x32_bf16 v[22:25], v[154:157], v[194:197], v[22:25]
	v_mfma_f32_16x16x32_bf16 v[14:17], v[146:149], v[202:205], v[14:17]
	v_mfma_f32_16x16x32_bf16 v[6:9], v[154:157], v[202:205], v[6:9]
	s_setprio 0
	s_setprio 1
	v_mfma_f32_16x16x32_bf16 v[58:61], v[158:161], v[174:177], v[58:61]
	v_mfma_f32_16x16x32_bf16 v[50:53], v[166:169], v[174:177], v[50:53]
	v_mfma_f32_16x16x32_bf16 v[42:45], v[158:161], v[182:185], v[42:45]
	v_mfma_f32_16x16x32_bf16 v[34:37], v[166:169], v[182:185], v[34:37]
	v_mfma_f32_16x16x32_bf16 v[26:29], v[158:161], v[190:193], v[26:29]
	v_mfma_f32_16x16x32_bf16 v[18:21], v[166:169], v[190:193], v[18:21]
	v_mfma_f32_16x16x32_bf16 v[10:13], v[158:161], v[198:201], v[10:13]
	v_mfma_f32_16x16x32_bf16 v[2:5], v[166:169], v[198:201], v[2:5]
	v_mfma_f32_16x16x32_bf16 v[58:61], v[162:165], v[178:181], v[58:61]
	v_mfma_f32_16x16x32_bf16 v[50:53], v[170:173], v[178:181], v[50:53]
	v_mfma_f32_16x16x32_bf16 v[42:45], v[162:165], v[186:189], v[42:45]
	v_mfma_f32_16x16x32_bf16 v[34:37], v[170:173], v[186:189], v[34:37]
	v_mfma_f32_16x16x32_bf16 v[26:29], v[162:165], v[194:197], v[26:29]
	v_mfma_f32_16x16x32_bf16 v[18:21], v[170:173], v[194:197], v[18:21]
	v_mfma_f32_16x16x32_bf16 v[10:13], v[162:165], v[202:205], v[10:13]
	v_mfma_f32_16x16x32_bf16 v[2:5], v[170:173], v[202:205], v[2:5]
	s_setprio 0
	s_barrier
	s_add_i32 s49, s49, 2
	s_add_u32 s45, s45, 0x100
	s_addc_u32 s48, s48, 0
	s_add_u32 s26, s26, 0x100
	s_addc_u32 s27, s27, 0
	s_cmp_gt_u32 s49, 29
	s_cbranch_scc1 .Lpeel_exit_G3

.Lpeel_exit_G3:
	s_mov_b32 s99, 1
	s_and_b64 vcc, exec, s[14:15]
	s_cbranch_vccz .LBB0_1063
	s_barrier
